# G1 tile order remapped: workgroup b takes panels (b&63)+64g with column tiles 4m+(b>>6), so 4 workgroups of an XCD share one A panel and 64 share a B tile at a time (L2 reuse)
# speedup vs baseline: 1.0045x; 1.0045x over previous
; #define PG8_STAGE(bufoff, gbase, voff) do { const char* _gb = (const char*)(gbase); asm volatile("" : "+s"(_gb)); _Pragma("unroll") for (int _i = 0; _i < 2; ++_i) \
;         __builtin_amdgcn_global_load_lds((const unsigned*)(_gb + (voff)[_i]), (LAS unsigned*)(lds + (bufoff) + ldsw + _i * 8192), 16, 0, 0); } while (0)
; #define PG8_WAIT_V(n) asm volatile("s_waitcnt vmcnt(" #n ")" ::: "memory")
; #define PG8_BAR __builtin_amdgcn_s_barrier()
; template <class Epi, class Sched>
; __device__ __forceinline__ void gemm_phase(LAS unsigned char* lds, const Gemm g, const Sched& S, const Epi& E) {
;     ...
;     for (int i = 0; i < 2; ++i) { int R, C; stage_rc(tid * 16 + i * 8192, R, C); const int Rb = Epi::PERM ? ((R & ~31) + perm32(R & 31)) : R;
;         voffA[i] = (unsigned)(R * lda + C) * 2u; voffB[i] = (unsigned)(Rb * K + C) * 2u; }
;     const size_t kstep = (size_t)(BK * 2);
;     const size_t hA = (size_t)HALF * lda * 2, hB = (size_t)HALF * K * 2;
;     const size_t tA = 2 * hA, tB = 2 * hB;
;     const unsigned ldsw = (unsigned)wid * 1024u;
;     const int aoff = lds_byte(wr * 64 + fr, fq * 8), boff = lds_byte(wc * 32 + fr, fq * 8);
;     ...
;     Unit cur, nxt; int ui = 0;
;     if (!S.next(0, cur)) return;
;     f32x4 acc[2][2][4][2];
; #pragma unroll
;     for (int a = 0; a < 2; ++a)
; #pragma unroll
;         for (int b = 0; b < 2; ++b)
; #pragma unroll
;             for (int m = 0; m < 4; ++m)
; #pragma unroll
;                 for (int n = 0; n < 2; ++n) acc[a][b][m][n] = (f32x4){0.f, 0.f, 0.f, 0.f};
;     bf16x8 At[4][2], B0[2][2], B1[2][2];
;     const char* cA = (const char*)g.A + (size_t)cur.pm * tA; const char* cB = (const char*)g.Bt + (size_t)cur.pn * tB;
;     PG8_STAGE(PG8_SB(0, 0), cB, voffB); PG8_STAGE(PG8_SA(0, 0), cA, voffA); PG8_STAGE(PG8_SB(0, 1), cB + hB, voffB); PG8_STAGE(PG8_SA(0, 1), cA + hA, voffA);
;     if (wr == 1) PG8_BAR;
;     PG8_WAIT_V(4); PG8_BAR;
;     PG8_STAGE(PG8_SB(1, 0), cB + kstep, voffB); PG8_STAGE(PG8_SA(1, 0), cA + kstep, voffA); PG8_STAGE(PG8_SB(1, 1), cB + hB + kstep, voffB);
;     PG8_WAIT_V(6); PG8_BAR;
.LBB0_69:
	s_cmp_lt_i32 s80, 2
	s_cselect_b64 s[0:1], -1, 0
	s_and_b64 s[4:5], s[0:1], s[8:9]
	s_andn2_b64 vcc, exec, s[4:5]
	s_cbranch_vccnz .LBB0_79
	v_mov_b32_e32 v0, v176
	s_mov_b32 s3, 0x1fffe0
	v_lshlrev_b32_e32 v1, 4, v0
	v_add_u32_e32 v2, 0x2000, v1
	v_ashrrev_i32_e32 v3, 31, v2
	v_lshrrev_b32_e32 v3, 22, v3
	v_add_u32_e32 v3, v2, v3
	v_ashrrev_i32_e32 v3, 10, v3
	v_mul_i32_i24_e32 v4, 0x400, v3
	v_sub_u32_e32 v2, v2, v4
	v_lshrrev_b32_e32 v4, 4, v2
	v_bitop3_b32 v2, v4, v2, 32 bitop3:0x6c
	v_ashrrev_i32_e32 v4, 31, v2
	v_lshrrev_b32_e32 v4, 26, v4
	v_add_u32_e32 v4, v2, v4
	v_lshlrev_b32_e32 v6, 3, v3
	v_ashrrev_i32_e32 v5, 6, v4
	v_and_b32_e32 v6, -16, v6
	v_and_b32_e32 v4, 0xc0, v4
	v_add_u32_e32 v6, v5, v6
	v_sub_u32_e32 v2, v2, v4
	v_mov_b32_e32 v4, 1
	v_and_b32_e32 v5, 3, v5
	v_lshrrev_b32_e32 v7, 2, v6
	v_lshlrev_b32_e32 v8, 1, v6
	v_lshlrev_b32_e32 v3, 5, v3
	v_ashrrev_i16_sdwa v2, v4, sext(v2) dst_sel:DWORD dst_unused:UNUSED_PAD src0_sel:DWORD src1_sel:BYTE_0
	v_and_or_b32 v5, v6, s3, v5
	v_and_b32_e32 v7, 4, v7
	v_and_b32_e32 v8, 24, v8
	v_and_b32_e32 v3, 32, v3
	v_bfe_i32 v2, v2, 0, 16
	v_or3_b32 v5, v5, v7, v8
	v_add_lshl_u32 v2, v3, v2, 1
	v_lshl_add_u32 v128, v5, 11, v2
	v_lshl_add_u32 v130, v6, 11, v2
	v_bfe_i32 v2, v0, 27, 1
	v_lshrrev_b32_e32 v2, 22, v2
	v_add_u32_e32 v2, v1, v2
	v_and_b32_e32 v2, 0xfffffc00, v2
	v_sub_u32_e32 v1, v1, v2
	v_lshrrev_b32_e32 v2, 4, v1
	v_ashrrev_i32_e32 v5, 31, v0
	v_bitop3_b32 v1, v2, v1, 32 bitop3:0x6c
	v_lshrrev_b32_e32 v5, 26, v5
	v_ashrrev_i32_e32 v2, 31, v1
	v_add_u32_e32 v5, v0, v5
	v_lshrrev_b32_e32 v2, 26, v2
	v_ashrrev_i32_e32 v5, 6, v5
	v_add_u32_e32 v2, v1, v2
	v_lshlrev_b32_e32 v6, 3, v5
	v_ashrrev_i32_e32 v3, 6, v2
	v_and_b32_e32 v6, -16, v6
	v_and_b32_e32 v2, 0xc0, v2
	s_add_u32 s4, s78, 0x18000000
	v_readfirstlane_b32 s20, v0
	v_add_u32_e32 v6, v3, v6
	v_sub_u32_e32 v1, v1, v2
	s_addc_u32 s5, s79, 0
	s_ashr_i32 s9, s20, 6
	v_and_b32_e32 v3, 3, v3
	v_lshrrev_b32_e32 v7, 2, v6
	v_lshlrev_b32_e32 v8, 1, v6
	v_lshlrev_b32_e32 v5, 5, v5
	v_ashrrev_i16_sdwa v1, v4, sext(v1) dst_sel:DWORD dst_unused:UNUSED_PAD src0_sel:DWORD src1_sel:BYTE_0
	s_lshl_b32 s21, s9, 10
	v_and_or_b32 v3, v6, s3, v3
	v_and_b32_e32 v7, 4, v7
	v_and_b32_e32 v8, 24, v8
	v_and_b32_e32 v5, 32, v5
	v_bfe_i32 v1, v1, 0, 16
	s_ashr_i32 s3, s2, 31
	v_or3_b32 v3, v3, v7, v8
	v_add_lshl_u32 v1, v5, v1, 1
	s_and_b32 s98, s2, 63
	s_mov_b32 s99, 0
	s_lshl_b64 s[6:7], s[98:99], 19
	s_add_i32 s3, s21, 0
	v_lshl_add_u32 v132, v3, 11, v1
	s_lshr_b32 s100, s2, 6
	s_lshl_b32 s100, s100, 19
	s_add_u32 s10, s4, s100
	s_addc_u32 s11, s5, 0
	s_add_i32 m0, s3, 0x10000
	s_ashr_i32 s8, s20, 8
	v_lshl_add_u32 v134, v6, 11, v1
	global_load_lds_dwordx4 v132, s[10:11]
	s_add_i32 m0, s3, 0x12000
	s_add_u32 s6, s76, s6
	s_addc_u32 s7, s77, s7
	global_load_lds_dwordx4 v128, s[10:11]
	s_mov_b64 s[10:11], s[6:7]
	s_mov_b32 m0, s3
	s_add_i32 s22, s3, 0x2000
	v_mov_b32_e32 v137, 0
	global_load_lds_dwordx4 v134, s[10:11]
	s_mov_b32 m0, s22
	s_mov_b32 s38, 0
	global_load_lds_dwordx4 v130, s[10:11]
	s_add_u32 s10, s78, 0x18040000
	s_addc_u32 s11, s79, 0
	s_add_u32 s10, s10, s100
	s_addc_u32 s11, s11, 0
	s_add_i32 m0, s3, 0x14000
	v_mov_b32_e32 v133, v137
	global_load_lds_dwordx4 v132, s[10:11]
	s_add_i32 m0, s3, 0x16000
	v_mov_b32_e32 v129, v137
	global_load_lds_dwordx4 v128, s[10:11]
	s_add_u32 s10, s6, 0x40000
	s_addc_u32 s11, s7, 0
	s_add_i32 s23, s3, 0x4000
	s_mov_b32 m0, s23
	s_add_i32 s24, s3, 0x6000
	v_mov_b32_e32 v135, v137
	global_load_lds_dwordx4 v134, s[10:11]
	s_mov_b32 m0, s24
	s_cmp_lg_u32 s8, 1
	global_load_lds_dwordx4 v130, s[10:11]
	v_mov_b32_e32 v131, v137
	s_cbranch_scc1 .LBB0_72
	s_barrier
.LBB0_72:
	s_and_b32 s12, s9, 3
	s_lshl_b32 s9, s8, 13
	s_lshl_b32 s13, s12, 12
	s_add_u32 s10, s78, 0x18000080
	s_addc_u32 s11, s79, 0
	s_add_u32 s10, s10, s100
	s_addc_u32 s11, s11, 0
	s_waitcnt vmcnt(4)
	s_barrier
	s_add_i32 m0, s3, 0x18000
	v_lshl_add_u64 v[2:3], s[10:11], 0, v[132:133]
	global_load_lds_dwordx4 v[2:3], off
	s_add_i32 m0, s3, 0x1a000
	v_lshl_add_u64 v[2:3], s[10:11], 0, v[128:129]
	s_add_u32 s10, s6, 0x80
	s_addc_u32 s11, s7, 0
	s_add_i32 s25, s3, 0x8000
	global_load_lds_dwordx4 v[2:3], off
	s_mov_b32 m0, s25
	v_lshl_add_u64 v[2:3], s[10:11], 0, v[134:135]
	s_add_i32 s26, s3, 0xa000
	global_load_lds_dwordx4 v[2:3], off
	v_lshl_add_u64 v[2:3], s[10:11], 0, v[130:131]
	s_add_u32 s10, s78, 0x18040080
	s_mov_b32 m0, s26
	s_addc_u32 s11, s79, 0
	s_add_u32 s10, s10, s100
	s_addc_u32 s11, s11, 0
	global_load_lds_dwordx4 v[2:3], off
	s_add_i32 m0, s3, 0x1c000
	v_lshl_add_u64 v[2:3], s[10:11], 0, v[132:133]
	global_load_lds_dwordx4 v[2:3], off
	v_lshl_add_u64 v[2:3], s[10:11], 0, v[128:129]
	s_add_i32 m0, s3, 0x1e000
	v_and_b32_e32 v1, 15, v0
	global_load_lds_dwordx4 v[2:3], off
	v_bfe_u32 v2, v0, 4, 2
	v_lshl_or_b32 v3, s8, 6, v1
	v_lshlrev_b32_e32 v4, 3, v2
	v_lshlrev_b32_e32 v2, 4, v2
	v_lshlrev_b32_e32 v0, 2, v0
	s_lshl_b32 s27, s2, 8
	v_lshl_or_b32 v1, v1, 6, v2
	v_and_b32_e32 v0, 32, v0
	s_and_b32 s101, s2, 63
	s_lshl_b32 s101, s101, 8
	v_add_u32_e32 v3, s101, v3
	v_bitop3_b32 v2, v1, s9, v0 bitop3:0xde
	v_bitop3_b32 v5, v1, s13, v0 bitop3:0xde
	s_waitcnt vmcnt(6)
	v_or_b32_e32 v6, 16, v3
	v_or_b32_e32 v7, 32, v3
	v_or_b32_e32 v8, 48, v3
	v_add_u32_e32 v9, 0x80, v3
	v_add_u32_e32 v10, 0x90, v3
	v_add_u32_e32 v11, 0xa0, v3
	v_add_u32_e32 v12, 0xb0, v3
	s_movk_i32 s10, 0x1800
	v_mov_b64_e32 v[0:1], s[78:79]
	s_add_i32 s30, 0, 0x10000
	s_add_i32 s33, 0, 0x14000
	v_mad_i64_i32 v[138:139], s[8:9], v3, s10, v[0:1]
	v_mad_i64_i32 v[140:141], s[8:9], v6, s10, v[0:1]
	v_mad_i64_i32 v[142:143], s[8:9], v7, s10, v[0:1]
	v_mad_i64_i32 v[144:145], s[8:9], v8, s10, v[0:1]
	v_mad_i64_i32 v[146:147], s[8:9], v9, s10, v[0:1]
	v_mad_i64_i32 v[148:149], s[8:9], v10, s10, v[0:1]
	v_mad_i64_i32 v[150:151], s[8:9], v11, s10, v[0:1]
	v_mad_i64_i32 v[152:153], s[8:9], v12, s10, v[0:1]
	v_lshl_or_b32 v0, s12, 5, v4
	v_add_u32_e32 v154, s30, v5
	v_add_u32_e32 v156, s33, v5
	s_add_i32 s30, s30, s21
	s_add_i32 s33, s33, s21
	s_add_i32 s35, 0, 0x18000
	s_add_i32 s36, 0, 0x1c000
	v_add_u32_e32 v155, 0, v2
	v_lshlrev_b32_e32 v157, 1, v0
	s_add_i32 s28, s3, 0xc000
	s_add_i32 s29, s3, 0xe000
	s_add_i32 s31, s30, 0x2000
	s_add_i32 s34, s33, 0x2000
	v_add_u32_e32 v158, s35, v5
	v_add_u32_e32 v159, s36, v5
	s_add_u32 s10, s4, s100
	s_addc_u32 s11, s5, 0
	s_mov_b64 s[98:99], s[6:7]
	s_barrier
; #define PG8_STAGE(bufoff, gbase, voff) do { const char* _gb = (const char*)(gbase); asm volatile("" : "+s"(_gb)); _Pragma("unroll") for (int _i = 0; _i < 2; ++_i) \
;         __builtin_amdgcn_global_load_lds((const unsigned*)(_gb + (voff)[_i]), (LAS unsigned*)(lds + (bufoff) + ldsw + _i * 8192), 16, 0, 0); } while (0)
; #define PG8_LDA(dst, b, h) do { _Pragma("unroll") for (int m = 0; m < 4; ++m) _Pragma("unroll") for (int k = 0; k < 2; ++k) dst[m][k] = *(const LAS bf16x8*)(lds + PG8_SA(b, h) + aoff + m * 2048 + k * 1024); } while (0)
; #define PG8_LDB(dst, b, h) do { _Pragma("unroll") for (int n = 0; n < 2; ++n) _Pragma("unroll") for (int k = 0; k < 2; ++k) dst[n][k] = *(const LAS bf16x8*)(lds + PG8_SB(b, h) + boff + n * 2048 + k * 1024); } while (0)
; #define PG8_SCHED __builtin_amdgcn_sched_barrier(0)
; template <class Epi, class Sched>
; __device__ __forceinline__ void gemm_phase(LAS unsigned char* lds, const Gemm g, const Sched& S, const Epi& E) {
;     ...
;         const bool has_next = S.next(ui + 1, nxt);
;         const char* nA = has_next ? (const char*)g.A + (size_t)nxt.pm * tA : cA; const char* nB = has_next ? (const char*)g.Bt + (size_t)nxt.pn * tB : cB;
;         for (int t = 0; t < nt; t += 2) {
;             const bool last = (t == nt - 2);
;             const char* a1 = cA + (size_t)(t + 1) * kstep;
;             const char* a2 = last ? nA : cA + (size_t)(t + 2) * kstep; const char* b2 = last ? nB : cB + (size_t)(t + 2) * kstep;
;             const char* a3 = a2 + kstep; const char* b3 = b2 + kstep;
;             PG8_LDB(B0, 0, 0); PG8_SCHED; PG8_LDA(At, 0, 0); PG8_STAGE(PG8_SA(1, 1), a1 + hA, voffA);
;     ...
; #pragma unroll
;         for (int a = 0; a < 2; ++a)
; #pragma unroll
;             for (int b = 0; b < 2; ++b)
; #pragma unroll
;                 for (int m = 0; m < 4; ++m)
; #pragma unroll
;                     for (int n = 0; n < 2; ++n) acc[a][b][m][n] = (f32x4){0.f, 0.f, 0.f, 0.f};
;         cur = nxt; cA = nA; cB = nB; ++ui;
.LBB0_73:
	s_mov_b32 s14, s37
	s_add_i32 s37, s38, 1
	s_cmp_lt_u32 s38, 11
	s_cselect_b64 s[12:13], -1, 0
	s_and_b64 s[8:9], s[12:13], exec
	s_cselect_b32 s8, s37, s14
	s_mul_i32 s100, s38, 0x5556
	s_lshr_b32 s100, s100, 16
	s_mul_i32 s101, s100, 3
	s_sub_u32 s101, s38, s101
	s_lshl_b32 s101, s101, 2
	s_lshr_b32 s9, s2, 6
	s_add_u32 s101, s101, s9
	s_lshl_b32 s101, s101, 9
	s_mul_i32 s100, s100, 0x6000000
	s_add_u32 s100, s100, s101
	s_mov_b64 s[6:7], s[98:99]
	s_mul_i32 s9, s8, 0x5556
	s_lshr_b32 s9, s9, 16
	s_mul_i32 s101, s9, 3
	s_sub_u32 s8, s8, s101
	s_cmp_eq_u32 s8, 0
	s_cselect_b32 s101, 0x2000000, 0
	s_add_u32 s98, s6, s101
	s_addc_u32 s99, s7, 0
	s_lshl_b32 s8, s8, 2
	s_lshr_b32 s101, s2, 6
	s_add_u32 s8, s8, s101
	s_ashr_i32 s9, s8, 31
	s_lshl_b64 s[8:9], s[8:9], 19
	s_add_u32 s8, s4, s8
	s_addc_u32 s9, s5, s9
	s_and_b64 s[12:13], s[12:13], exec
	s_cselect_b32 s39, s9, s11
	s_cselect_b32 s40, s8, s10
	s_add_u32 s41, s10, 0x100
	v_mov_b32_e32 v0, 0
	s_addc_u32 s42, s11, 0
	s_mov_b32 s43, -2
	s_mov_b64 s[10:11], s[6:7]
	v_mov_b32_e32 v1, v0
	v_mov_b32_e32 v2, v0
	v_mov_b32_e32 v3, v0
	v_mov_b32_e32 v4, v0
	v_mov_b32_e32 v5, v0
	v_mov_b32_e32 v6, v0
	v_mov_b32_e32 v7, v0
	v_mov_b32_e32 v8, v0
	v_mov_b32_e32 v9, v0
	v_mov_b32_e32 v10, v0
	v_mov_b32_e32 v11, v0
	v_mov_b32_e32 v16, v0
	v_mov_b32_e32 v17, v0
	v_mov_b32_e32 v18, v0
	v_mov_b32_e32 v19, v0
	v_mov_b32_e32 v24, v0
	v_mov_b32_e32 v25, v0
	v_mov_b32_e32 v26, v0
	v_mov_b32_e32 v27, v0
	v_mov_b32_e32 v32, v0
	v_mov_b32_e32 v33, v0
	v_mov_b32_e32 v34, v0
	v_mov_b32_e32 v35, v0
	v_mov_b32_e32 v40, v0
	v_mov_b32_e32 v41, v0
	v_mov_b32_e32 v42, v0
	v_mov_b32_e32 v43, v0
	v_mov_b32_e32 v48, v0
	v_mov_b32_e32 v49, v0
	v_mov_b32_e32 v50, v0
	v_mov_b32_e32 v51, v0
	v_mov_b32_e32 v12, v0
	v_mov_b32_e32 v13, v0
	v_mov_b32_e32 v14, v0
	v_mov_b32_e32 v15, v0
	v_mov_b32_e32 v20, v0
	v_mov_b32_e32 v21, v0
	v_mov_b32_e32 v22, v0
	v_mov_b32_e32 v23, v0
	v_mov_b32_e32 v28, v0
	v_mov_b32_e32 v29, v0
	v_mov_b32_e32 v30, v0
	v_mov_b32_e32 v31, v0
	v_mov_b32_e32 v36, v0
	v_mov_b32_e32 v37, v0
	v_mov_b32_e32 v38, v0
	v_mov_b32_e32 v39, v0
	v_mov_b32_e32 v44, v0
	v_mov_b32_e32 v45, v0
	v_mov_b32_e32 v46, v0
	v_mov_b32_e32 v47, v0
	v_mov_b32_e32 v52, v0
	v_mov_b32_e32 v53, v0
	v_mov_b32_e32 v54, v0
	v_mov_b32_e32 v55, v0
	v_mov_b32_e32 v56, v0
	v_mov_b32_e32 v57, v0
	v_mov_b32_e32 v58, v0
	v_mov_b32_e32 v59, v0
	v_mov_b32_e32 v60, v0
	v_mov_b32_e32 v61, v0
	v_mov_b32_e32 v62, v0
	v_mov_b32_e32 v63, v0
	v_mov_b32_e32 v64, v0
	v_mov_b32_e32 v65, v0
	v_mov_b32_e32 v66, v0
	v_mov_b32_e32 v67, v0
	v_mov_b32_e32 v68, v0
	v_mov_b32_e32 v69, v0
	v_mov_b32_e32 v70, v0
	v_mov_b32_e32 v71, v0
	v_mov_b32_e32 v72, v0
	v_mov_b32_e32 v73, v0
	v_mov_b32_e32 v74, v0
	v_mov_b32_e32 v75, v0
	v_mov_b32_e32 v80, v0
	v_mov_b32_e32 v81, v0
	v_mov_b32_e32 v82, v0
	v_mov_b32_e32 v83, v0
	v_mov_b32_e32 v88, v0
	v_mov_b32_e32 v89, v0
	v_mov_b32_e32 v90, v0
	v_mov_b32_e32 v91, v0
	v_mov_b32_e32 v96, v0
	v_mov_b32_e32 v97, v0
	v_mov_b32_e32 v98, v0
	v_mov_b32_e32 v99, v0
	v_mov_b32_e32 v104, v0
	v_mov_b32_e32 v105, v0
	v_mov_b32_e32 v106, v0
	v_mov_b32_e32 v107, v0
	v_mov_b32_e32 v112, v0
	v_mov_b32_e32 v113, v0
	v_mov_b32_e32 v114, v0
	v_mov_b32_e32 v115, v0
	v_mov_b32_e32 v76, v0
	v_mov_b32_e32 v77, v0
	v_mov_b32_e32 v78, v0
	v_mov_b32_e32 v79, v0
	v_mov_b32_e32 v84, v0
	v_mov_b32_e32 v85, v0
	v_mov_b32_e32 v86, v0
	v_mov_b32_e32 v87, v0
	v_mov_b32_e32 v92, v0
	v_mov_b32_e32 v93, v0
	v_mov_b32_e32 v94, v0
	v_mov_b32_e32 v95, v0
	v_mov_b32_e32 v100, v0
	v_mov_b32_e32 v101, v0
	v_mov_b32_e32 v102, v0
	v_mov_b32_e32 v103, v0
	v_mov_b32_e32 v108, v0
	v_mov_b32_e32 v109, v0
	v_mov_b32_e32 v110, v0
	v_mov_b32_e32 v111, v0
	v_mov_b32_e32 v116, v0
	v_mov_b32_e32 v117, v0
	v_mov_b32_e32 v118, v0
	v_mov_b32_e32 v119, v0
	v_mov_b32_e32 v120, v0
	v_mov_b32_e32 v121, v0
	v_mov_b32_e32 v122, v0
	v_mov_b32_e32 v123, v0
	v_mov_b32_e32 v124, v0
	v_mov_b32_e32 v125, v0
	v_mov_b32_e32 v126, v0
	v_mov_b32_e32 v127, v0
.LBB0_74:
	ds_read_b128 v[160:163], v154
	ds_read_b128 v[164:167], v154 offset:1024
	ds_read_b128 v[168:171], v154 offset:2048
	ds_read_b128 v[172:175], v154 offset:3072
	s_add_u32 s12, s10, 0x100
	s_addc_u32 s13, s11, 0
	s_cmp_eq_u32 s43, 12
	s_cselect_b32 s18, s98, s12
	s_cselect_b32 s19, s99, s13
	s_cselect_b32 s14, s40, s41
	s_cselect_b32 s15, s39, s42
	s_add_u32 s16, s18, 0x80
	s_addc_u32 s17, s19, 0
	s_add_u32 s10, s10, 0x40080
	s_addc_u32 s11, s11, 0
	s_mov_b32 m0, s28
	ds_read_b128 v[178:181], v155
	ds_read_b128 v[182:185], v155 offset:1024
	ds_read_b128 v[186:189], v155 offset:2048
	ds_read_b128 v[190:193], v155 offset:3072
	ds_read_b128 v[194:197], v155 offset:4096
	ds_read_b128 v[198:201], v155 offset:5120
	ds_read_b128 v[202:205], v155 offset:6144
	ds_read_b128 v[206:209], v155 offset:7168
	s_nop 0
	v_lshl_add_u64 v[210:211], s[10:11], 0, v[134:135]
	global_load_lds_dwordx4 v[210:211], off
	v_lshl_add_u64 v[210:211], s[10:11], 0, v[130:131]
	s_mov_b32 m0, s29
	s_nop 0
	global_load_lds_dwordx4 v[210:211], off
	s_waitcnt lgkmcnt(8)
	s_barrier
; #define PG8_STAGE(bufoff, gbase, voff) do { const char* _gb = (const char*)(gbase); asm volatile("" : "+s"(_gb)); _Pragma("unroll") for (int _i = 0; _i < 2; ++_i) \
;         __builtin_amdgcn_global_load_lds((const unsigned*)(_gb + (voff)[_i]), (LAS unsigned*)(lds + (bufoff) + ldsw + _i * 8192), 16, 0, 0); } while (0)
; #define PG8_LDA(dst, b, h) do { _Pragma("unroll") for (int m = 0; m < 4; ++m) _Pragma("unroll") for (int k = 0; k < 2; ++k) dst[m][k] = *(const LAS bf16x8*)(lds + PG8_SA(b, h) + aoff + m * 2048 + k * 1024); } while (0)
; #define PG8_LDB(dst, b, h) do { _Pragma("unroll") for (int n = 0; n < 2; ++n) _Pragma("unroll") for (int k = 0; k < 2; ++k) dst[n][k] = *(const LAS bf16x8*)(lds + PG8_SB(b, h) + boff + n * 2048 + k * 1024); } while (0)
; #define PG8_MMA(ai, bj, At, Bt) do { __builtin_amdgcn_s_setprio(1); _Pragma("unroll") for (int m = 0; m < 4; ++m) _Pragma("unroll") for (int n = 0; n < 2; ++n) _Pragma("unroll") for (int k = 0; k < 2; ++k) \
;         acc[ai][bj][m][n] = __builtin_amdgcn_mfma_f32_16x16x32_bf16(Bt[n][k], At[m][k], acc[ai][bj][m][n], 0, 0, 0); __builtin_amdgcn_s_setprio(0); } while (0)
; #define PG8_WAIT_V(n) asm volatile("s_waitcnt vmcnt(" #n ")" ::: "memory")
; #define PG8_WAIT_L(n) asm volatile("s_waitcnt lgkmcnt(" #n ")" ::: "memory")
; #define PG8_BAR __builtin_amdgcn_s_barrier()
; #define PG8_SCHED __builtin_amdgcn_sched_barrier(0)
; template <class Epi, class Sched>
; __device__ __forceinline__ void gemm_phase(LAS unsigned char* lds, const Gemm g, const Sched& S, const Epi& E) {
;     ...
;             PG8_WAIT_L(8); PG8_BAR; PG8_WAIT_L(0); PG8_MMA(0, 0, At, B0); PG8_BAR; PG8_SCHED;
;             PG8_LDB(B1, 0, 1); PG8_STAGE(PG8_SB(0, 0), b2, voffB);
;             PG8_BAR; PG8_WAIT_L(0); PG8_MMA(0, 1, At, B1); PG8_BAR;
;             PG8_LDA(At, 0, 1); PG8_STAGE(PG8_SA(0, 0), a2, voffA);
;             PG8_BAR; PG8_WAIT_L(0); PG8_MMA(1, 0, At, B0); PG8_BAR; PG8_SCHED;
;             PG8_STAGE(PG8_SB(0, 1), b2 + hB, voffB);
;             PG8_WAIT_V(6); PG8_BAR; PG8_MMA(1, 1, At, B1); PG8_BAR;
	s_waitcnt lgkmcnt(0)
	s_setprio 1
	s_waitcnt lgkmcnt(0)
	v_mfma_f32_16x16x32_bf16 v[124:127], v[160:163], v[178:181], v[124:127]
	v_mfma_f32_16x16x32_bf16 v[120:123], v[168:171], v[178:181], v[120:123]
	v_mfma_f32_16x16x32_bf16 v[116:119], v[160:163], v[186:189], v[116:119]
	v_mfma_f32_16x16x32_bf16 v[108:111], v[168:171], v[186:189], v[108:111]
	v_mfma_f32_16x16x32_bf16 v[100:103], v[160:163], v[194:197], v[100:103]
	v_mfma_f32_16x16x32_bf16 v[92:95], v[168:171], v[194:197], v[92:95]
	v_mfma_f32_16x16x32_bf16 v[84:87], v[160:163], v[202:205], v[84:87]
	v_mfma_f32_16x16x32_bf16 v[76:79], v[168:171], v[202:205], v[76:79]
	v_mfma_f32_16x16x32_bf16 v[124:127], v[164:167], v[182:185], v[124:127]
	v_mfma_f32_16x16x32_bf16 v[120:123], v[172:175], v[182:185], v[120:123]
	v_mfma_f32_16x16x32_bf16 v[116:119], v[164:167], v[190:193], v[116:119]
	v_mfma_f32_16x16x32_bf16 v[108:111], v[172:175], v[190:193], v[108:111]
	v_mfma_f32_16x16x32_bf16 v[100:103], v[164:167], v[198:201], v[100:103]
	v_mfma_f32_16x16x32_bf16 v[92:95], v[172:175], v[198:201], v[92:95]
	v_mfma_f32_16x16x32_bf16 v[84:87], v[164:167], v[206:209], v[84:87]
	v_mfma_f32_16x16x32_bf16 v[76:79], v[172:175], v[206:209], v[76:79]
	s_setprio 0
	s_barrier
	s_mov_b64 s[10:11], s[14:15]
	s_mov_b32 m0, s30
	ds_read_b128 v[210:213], v156
	ds_read_b128 v[214:217], v156 offset:1024
	ds_read_b128 v[218:221], v156 offset:2048
	ds_read_b128 v[222:225], v156 offset:3072
	s_nop 0
	v_lshl_add_u64 v[226:227], s[10:11], 0, v[132:133]
	global_load_lds_dwordx4 v[226:227], off
	v_lshl_add_u64 v[226:227], s[10:11], 0, v[128:129]
	s_mov_b32 m0, s31
	s_nop 0
	global_load_lds_dwordx4 v[226:227], off
	s_barrier
	s_waitcnt lgkmcnt(0)
	s_setprio 1
	s_waitcnt lgkmcnt(0)
	v_mfma_f32_16x16x32_bf16 v[112:115], v[210:213], v[178:181], v[112:115]
	v_mfma_f32_16x16x32_bf16 v[104:107], v[218:221], v[178:181], v[104:107]
	v_mfma_f32_16x16x32_bf16 v[96:99], v[210:213], v[186:189], v[96:99]
	v_mfma_f32_16x16x32_bf16 v[88:91], v[218:221], v[186:189], v[88:91]
	v_mfma_f32_16x16x32_bf16 v[80:83], v[210:213], v[194:197], v[80:83]
	v_mfma_f32_16x16x32_bf16 v[72:75], v[218:221], v[194:197], v[72:75]
	v_mfma_f32_16x16x32_bf16 v[68:71], v[210:213], v[202:205], v[68:71]
	v_mfma_f32_16x16x32_bf16 v[64:67], v[218:221], v[202:205], v[64:67]
	v_mfma_f32_16x16x32_bf16 v[112:115], v[214:217], v[182:185], v[112:115]
	v_mfma_f32_16x16x32_bf16 v[104:107], v[222:225], v[182:185], v[104:107]
	v_mfma_f32_16x16x32_bf16 v[96:99], v[214:217], v[190:193], v[96:99]
	v_mfma_f32_16x16x32_bf16 v[88:91], v[222:225], v[190:193], v[88:91]
	v_mfma_f32_16x16x32_bf16 v[80:83], v[214:217], v[198:201], v[80:83]
	v_mfma_f32_16x16x32_bf16 v[72:75], v[222:225], v[198:201], v[72:75]
	v_mfma_f32_16x16x32_bf16 v[68:71], v[214:217], v[206:209], v[68:71]
	v_mfma_f32_16x16x32_bf16 v[64:67], v[222:225], v[206:209], v[64:67]
	s_setprio 0
	s_mov_b64 s[10:11], s[18:19]
	s_mov_b32 m0, s3
	s_barrier
	ds_read_b128 v[178:181], v155 offset:16384
	ds_read_b128 v[182:185], v155 offset:17408
	ds_read_b128 v[186:189], v155 offset:18432
	ds_read_b128 v[190:193], v155 offset:19456
	ds_read_b128 v[194:197], v155 offset:20480
	ds_read_b128 v[198:201], v155 offset:21504
	ds_read_b128 v[202:205], v155 offset:22528
	ds_read_b128 v[206:209], v155 offset:23552
	s_nop 0
	v_lshl_add_u64 v[226:227], s[10:11], 0, v[134:135]
	global_load_lds_dwordx4 v[226:227], off
	v_lshl_add_u64 v[226:227], s[10:11], 0, v[130:131]
	s_mov_b32 m0, s22
	s_nop 0
	global_load_lds_dwordx4 v[226:227], off
	s_barrier
	s_waitcnt lgkmcnt(0)
	s_setprio 1
	s_waitcnt lgkmcnt(0)
	v_mfma_f32_16x16x32_bf16 v[60:63], v[160:163], v[178:181], v[60:63]
	v_mfma_f32_16x16x32_bf16 v[56:59], v[168:171], v[178:181], v[56:59]
	v_mfma_f32_16x16x32_bf16 v[52:55], v[160:163], v[186:189], v[52:55]
	v_mfma_f32_16x16x32_bf16 v[44:47], v[168:171], v[186:189], v[44:47]
	v_mfma_f32_16x16x32_bf16 v[36:39], v[160:163], v[194:197], v[36:39]
	v_mfma_f32_16x16x32_bf16 v[28:31], v[168:171], v[194:197], v[28:31]
	v_mfma_f32_16x16x32_bf16 v[20:23], v[160:163], v[202:205], v[20:23]
	v_mfma_f32_16x16x32_bf16 v[12:15], v[168:171], v[202:205], v[12:15]
	v_mfma_f32_16x16x32_bf16 v[60:63], v[164:167], v[182:185], v[60:63]
	v_mfma_f32_16x16x32_bf16 v[56:59], v[172:175], v[182:185], v[56:59]
	v_mfma_f32_16x16x32_bf16 v[52:55], v[164:167], v[190:193], v[52:55]
	v_mfma_f32_16x16x32_bf16 v[44:47], v[172:175], v[190:193], v[44:47]
	v_mfma_f32_16x16x32_bf16 v[36:39], v[164:167], v[198:201], v[36:39]
	v_mfma_f32_16x16x32_bf16 v[28:31], v[172:175], v[198:201], v[28:31]
	v_mfma_f32_16x16x32_bf16 v[20:23], v[164:167], v[206:209], v[20:23]
	v_mfma_f32_16x16x32_bf16 v[12:15], v[172:175], v[206:209], v[12:15]
	s_setprio 0
	s_barrier
	s_add_u32 s10, s14, 0x40000
	s_addc_u32 s11, s15, 0
	s_mov_b32 m0, s33
	s_nop 0
	v_lshl_add_u64 v[160:161], s[10:11], 0, v[132:133]
	global_load_lds_dwordx4 v[160:161], off
	v_lshl_add_u64 v[160:161], s[10:11], 0, v[128:129]
	s_mov_b32 m0, s34
	s_nop 0
	global_load_lds_dwordx4 v[160:161], off
	s_waitcnt vmcnt(6)
	s_barrier
	s_setprio 1
	v_mfma_f32_16x16x32_bf16 v[48:51], v[210:213], v[178:181], v[48:51]
	v_mfma_f32_16x16x32_bf16 v[40:43], v[218:221], v[178:181], v[40:43]
	v_mfma_f32_16x16x32_bf16 v[32:35], v[210:213], v[186:189], v[32:35]
	v_mfma_f32_16x16x32_bf16 v[24:27], v[218:221], v[186:189], v[24:27]
	v_mfma_f32_16x16x32_bf16 v[16:19], v[210:213], v[194:197], v[16:19]
	v_mfma_f32_16x16x32_bf16 v[8:11], v[218:221], v[194:197], v[8:11]
	v_mfma_f32_16x16x32_bf16 v[4:7], v[210:213], v[202:205], v[4:7]
	v_mfma_f32_16x16x32_bf16 v[0:3], v[218:221], v[202:205], v[0:3]
	v_mfma_f32_16x16x32_bf16 v[48:51], v[214:217], v[182:185], v[48:51]
	v_mfma_f32_16x16x32_bf16 v[40:43], v[222:225], v[182:185], v[40:43]
	v_mfma_f32_16x16x32_bf16 v[32:35], v[214:217], v[190:193], v[32:35]
	v_mfma_f32_16x16x32_bf16 v[24:27], v[222:225], v[190:193], v[24:27]
	v_mfma_f32_16x16x32_bf16 v[16:19], v[214:217], v[198:201], v[16:19]
	v_mfma_f32_16x16x32_bf16 v[8:11], v[222:225], v[198:201], v[8:11]
	v_mfma_f32_16x16x32_bf16 v[4:7], v[214:217], v[206:209], v[4:7]
	v_mfma_f32_16x16x32_bf16 v[0:3], v[222:225], v[206:209], v[0:3]
	s_setprio 0
	s_barrier
; #define PG8_STAGE(bufoff, gbase, voff) do { const char* _gb = (const char*)(gbase); asm volatile("" : "+s"(_gb)); _Pragma("unroll") for (int _i = 0; _i < 2; ++_i) \
;         __builtin_amdgcn_global_load_lds((const unsigned*)(_gb + (voff)[_i]), (LAS unsigned*)(lds + (bufoff) + ldsw + _i * 8192), 16, 0, 0); } while (0)
; #define PG8_LDA(dst, b, h) do { _Pragma("unroll") for (int m = 0; m < 4; ++m) _Pragma("unroll") for (int k = 0; k < 2; ++k) dst[m][k] = *(const LAS bf16x8*)(lds + PG8_SA(b, h) + aoff + m * 2048 + k * 1024); } while (0)
; #define PG8_LDB(dst, b, h) do { _Pragma("unroll") for (int n = 0; n < 2; ++n) _Pragma("unroll") for (int k = 0; k < 2; ++k) dst[n][k] = *(const LAS bf16x8*)(lds + PG8_SB(b, h) + boff + n * 2048 + k * 1024); } while (0)
; #define PG8_MMA(ai, bj, At, Bt) do { __builtin_amdgcn_s_setprio(1); _Pragma("unroll") for (int m = 0; m < 4; ++m) _Pragma("unroll") for (int n = 0; n < 2; ++n) _Pragma("unroll") for (int k = 0; k < 2; ++k) \
;         acc[ai][bj][m][n] = __builtin_amdgcn_mfma_f32_16x16x32_bf16(Bt[n][k], At[m][k], acc[ai][bj][m][n], 0, 0, 0); __builtin_amdgcn_s_setprio(0); } while (0)
; #define PG8_WAIT_L(n) asm volatile("s_waitcnt lgkmcnt(" #n ")" ::: "memory")
; #define PG8_BAR __builtin_amdgcn_s_barrier()
; #define PG8_SCHED __builtin_amdgcn_sched_barrier(0)
; template <class Epi, class Sched>
; __device__ __forceinline__ void gemm_phase(LAS unsigned char* lds, const Gemm g, const Sched& S, const Epi& E) {
;     ...
;             PG8_LDB(B0, 1, 0); PG8_SCHED; PG8_LDA(At, 1, 0); PG8_STAGE(PG8_SA(0, 1), a2 + hA, voffA);
;             PG8_WAIT_L(8); PG8_BAR; PG8_WAIT_L(0); PG8_MMA(0, 0, At, B0); PG8_BAR; PG8_SCHED;
;             PG8_LDB(B1, 1, 1); PG8_STAGE(PG8_SB(1, 0), b3, voffB);
;             PG8_BAR; PG8_WAIT_L(0); PG8_MMA(0, 1, At, B1); PG8_BAR;
;             PG8_LDA(At, 1, 1); PG8_STAGE(PG8_SA(1, 0), a3, voffA);
;             PG8_BAR; PG8_WAIT_L(0); PG8_MMA(1, 0, At, B0); PG8_BAR; PG8_SCHED;
	ds_read_b128 v[160:163], v158
	ds_read_b128 v[164:167], v158 offset:1024
	ds_read_b128 v[168:171], v158 offset:2048
	ds_read_b128 v[172:175], v158 offset:3072
	s_add_u32 s10, s18, 0x40000
	s_addc_u32 s11, s19, 0
	s_mov_b32 m0, s23
	ds_read_b128 v[178:181], v155 offset:32768
	ds_read_b128 v[182:185], v155 offset:33792
	ds_read_b128 v[186:189], v155 offset:34816
	ds_read_b128 v[190:193], v155 offset:35840
	ds_read_b128 v[194:197], v155 offset:36864
	ds_read_b128 v[198:201], v155 offset:37888
	ds_read_b128 v[202:205], v155 offset:38912
	ds_read_b128 v[206:209], v155 offset:39936
	s_nop 0
	v_lshl_add_u64 v[210:211], s[10:11], 0, v[134:135]
	global_load_lds_dwordx4 v[210:211], off
	v_lshl_add_u64 v[210:211], s[10:11], 0, v[130:131]
	s_mov_b32 m0, s24
	s_nop 0
	global_load_lds_dwordx4 v[210:211], off
	s_waitcnt lgkmcnt(8)
	s_barrier
	s_waitcnt lgkmcnt(0)
	s_setprio 1
	s_waitcnt lgkmcnt(0)
	v_mfma_f32_16x16x32_bf16 v[124:127], v[160:163], v[178:181], v[124:127]
	v_mfma_f32_16x16x32_bf16 v[120:123], v[168:171], v[178:181], v[120:123]
	v_mfma_f32_16x16x32_bf16 v[116:119], v[160:163], v[186:189], v[116:119]
	v_mfma_f32_16x16x32_bf16 v[108:111], v[168:171], v[186:189], v[108:111]
	v_mfma_f32_16x16x32_bf16 v[100:103], v[160:163], v[194:197], v[100:103]
	v_mfma_f32_16x16x32_bf16 v[92:95], v[168:171], v[194:197], v[92:95]
	v_mfma_f32_16x16x32_bf16 v[84:87], v[160:163], v[202:205], v[84:87]
	v_mfma_f32_16x16x32_bf16 v[76:79], v[168:171], v[202:205], v[76:79]
	v_mfma_f32_16x16x32_bf16 v[124:127], v[164:167], v[182:185], v[124:127]
	v_mfma_f32_16x16x32_bf16 v[120:123], v[172:175], v[182:185], v[120:123]
	v_mfma_f32_16x16x32_bf16 v[116:119], v[164:167], v[190:193], v[116:119]
	v_mfma_f32_16x16x32_bf16 v[108:111], v[172:175], v[190:193], v[108:111]
	v_mfma_f32_16x16x32_bf16 v[100:103], v[164:167], v[198:201], v[100:103]
	v_mfma_f32_16x16x32_bf16 v[92:95], v[172:175], v[198:201], v[92:95]
	v_mfma_f32_16x16x32_bf16 v[84:87], v[164:167], v[206:209], v[84:87]
	v_mfma_f32_16x16x32_bf16 v[76:79], v[172:175], v[206:209], v[76:79]
	s_setprio 0
	s_barrier
	s_add_u32 s10, s14, 0x80
	s_addc_u32 s11, s15, 0
	s_add_i32 s18, s35, s21
	ds_read_b128 v[210:213], v159
	ds_read_b128 v[214:217], v159 offset:1024
	ds_read_b128 v[218:221], v159 offset:2048
	ds_read_b128 v[222:225], v159 offset:3072
	s_mov_b32 m0, s18
	v_lshl_add_u64 v[226:227], s[10:11], 0, v[132:133]
	global_load_lds_dwordx4 v[226:227], off
	v_lshl_add_u64 v[226:227], s[10:11], 0, v[128:129]
	s_add_i32 m0, s18, 0x2000
	s_nop 0
	global_load_lds_dwordx4 v[226:227], off
	s_barrier
	s_waitcnt lgkmcnt(0)
	s_setprio 1
	s_waitcnt lgkmcnt(0)
	v_mfma_f32_16x16x32_bf16 v[112:115], v[210:213], v[178:181], v[112:115]
	v_mfma_f32_16x16x32_bf16 v[104:107], v[218:221], v[178:181], v[104:107]
	v_mfma_f32_16x16x32_bf16 v[96:99], v[210:213], v[186:189], v[96:99]
	v_mfma_f32_16x16x32_bf16 v[88:91], v[218:221], v[186:189], v[88:91]
	v_mfma_f32_16x16x32_bf16 v[80:83], v[210:213], v[194:197], v[80:83]
	v_mfma_f32_16x16x32_bf16 v[72:75], v[218:221], v[194:197], v[72:75]
	v_mfma_f32_16x16x32_bf16 v[68:71], v[210:213], v[202:205], v[68:71]
	v_mfma_f32_16x16x32_bf16 v[64:67], v[218:221], v[202:205], v[64:67]
	v_mfma_f32_16x16x32_bf16 v[112:115], v[214:217], v[182:185], v[112:115]
	v_mfma_f32_16x16x32_bf16 v[104:107], v[222:225], v[182:185], v[104:107]
	v_mfma_f32_16x16x32_bf16 v[96:99], v[214:217], v[190:193], v[96:99]
	v_mfma_f32_16x16x32_bf16 v[88:91], v[222:225], v[190:193], v[88:91]
	v_mfma_f32_16x16x32_bf16 v[80:83], v[214:217], v[198:201], v[80:83]
	v_mfma_f32_16x16x32_bf16 v[72:75], v[222:225], v[198:201], v[72:75]
	v_mfma_f32_16x16x32_bf16 v[68:71], v[214:217], v[206:209], v[68:71]
	v_mfma_f32_16x16x32_bf16 v[64:67], v[222:225], v[206:209], v[64:67]
	s_setprio 0
	s_mov_b32 m0, s25
	s_barrier
	ds_read_b128 v[178:181], v155 offset:49152
	ds_read_b128 v[182:185], v155 offset:50176
	ds_read_b128 v[186:189], v155 offset:51200
	ds_read_b128 v[190:193], v155 offset:52224
	ds_read_b128 v[194:197], v155 offset:53248
	ds_read_b128 v[198:201], v155 offset:54272
	ds_read_b128 v[202:205], v155 offset:55296
	ds_read_b128 v[206:209], v155 offset:56320
	s_nop 0
	v_lshl_add_u64 v[226:227], s[16:17], 0, v[134:135]
	global_load_lds_dwordx4 v[226:227], off
	v_lshl_add_u64 v[226:227], s[16:17], 0, v[130:131]
	s_mov_b32 m0, s26
	s_nop 0
	global_load_lds_dwordx4 v[226:227], off
	s_barrier
	s_waitcnt lgkmcnt(0)
	s_setprio 1
	s_waitcnt lgkmcnt(0)
	v_mfma_f32_16x16x32_bf16 v[60:63], v[160:163], v[178:181], v[60:63]
	v_mfma_f32_16x16x32_bf16 v[56:59], v[168:171], v[178:181], v[56:59]
	v_mfma_f32_16x16x32_bf16 v[52:55], v[160:163], v[186:189], v[52:55]
	v_mfma_f32_16x16x32_bf16 v[44:47], v[168:171], v[186:189], v[44:47]
	v_mfma_f32_16x16x32_bf16 v[36:39], v[160:163], v[194:197], v[36:39]
	v_mfma_f32_16x16x32_bf16 v[28:31], v[168:171], v[194:197], v[28:31]
	v_mfma_f32_16x16x32_bf16 v[20:23], v[160:163], v[202:205], v[20:23]
	v_mfma_f32_16x16x32_bf16 v[12:15], v[168:171], v[202:205], v[12:15]
	v_mfma_f32_16x16x32_bf16 v[60:63], v[164:167], v[182:185], v[60:63]
	v_mfma_f32_16x16x32_bf16 v[56:59], v[172:175], v[182:185], v[56:59]
	v_mfma_f32_16x16x32_bf16 v[52:55], v[164:167], v[190:193], v[52:55]
	v_mfma_f32_16x16x32_bf16 v[44:47], v[172:175], v[190:193], v[44:47]
	v_mfma_f32_16x16x32_bf16 v[36:39], v[164:167], v[198:201], v[36:39]
	v_mfma_f32_16x16x32_bf16 v[28:31], v[172:175], v[198:201], v[28:31]
	v_mfma_f32_16x16x32_bf16 v[20:23], v[164:167], v[206:209], v[20:23]
	v_mfma_f32_16x16x32_bf16 v[12:15], v[172:175], v[206:209], v[12:15]
	s_setprio 0
	s_barrier
; __device__ __forceinline__ unsigned cvt_pk(float lo, float hi) { unsigned r; asm volatile("v_cvt_pk_bf16_f32 %0, %1, %2" : "=v"(r) : "v"(lo), "v"(hi)); return r; }
; #define PG8_STAGE(bufoff, gbase, voff) do { const char* _gb = (const char*)(gbase); asm volatile("" : "+s"(_gb)); _Pragma("unroll") for (int _i = 0; _i < 2; ++_i) \
;         __builtin_amdgcn_global_load_lds((const unsigned*)(_gb + (voff)[_i]), (LAS unsigned*)(lds + (bufoff) + ldsw + _i * 8192), 16, 0, 0); } while (0)
; #define PG8_MMA(ai, bj, At, Bt) do { __builtin_amdgcn_s_setprio(1); _Pragma("unroll") for (int m = 0; m < 4; ++m) _Pragma("unroll") for (int n = 0; n < 2; ++n) _Pragma("unroll") for (int k = 0; k < 2; ++k) \
;         acc[ai][bj][m][n] = __builtin_amdgcn_mfma_f32_16x16x32_bf16(Bt[n][k], At[m][k], acc[ai][bj][m][n], 0, 0, 0); __builtin_amdgcn_s_setprio(0); } while (0)
; #define PG8_WAIT_V(n) asm volatile("s_waitcnt vmcnt(" #n ")" ::: "memory")
; #define PG8_BAR __builtin_amdgcn_s_barrier()
; template <class Epi, class Sched>
; __device__ __forceinline__ void gemm_phase(LAS unsigned char* lds, const Gemm g, const Sched& S, const Epi& E) {
;     ...
;             PG8_STAGE(PG8_SB(1, 1), b3 + hB, voffB);
;             PG8_WAIT_V(6); PG8_BAR; PG8_MMA(1, 1, At, B1); PG8_BAR;
;         }
;         E(acc, cur, wr, wc, fr, fq);
;     __device__ __forceinline__ void operator()(const f32x4 (&acc)[2][2][4][2], const Unit& u, int wr, int wc, int fr, int fq) const {
;         const int row0 = u.pm * BM + wr * 64 + fr;
;         if (u.pn < 12) {
;             const int col0 = u.pn * BM + wc * 32 + 8 * fq;
; #pragma unroll
;             for (int ai = 0; ai < 2; ++ai)
; #pragma unroll
;                 for (int m = 0; m < 4; ++m) { bf16_t* rowp = P0 + (size_t)(row0 + ai * HALF + m * 16) * LDP + col0;
; #pragma unroll
;                     for (int bj = 0; bj < 2; ++bj) { const f32x4 v0 = acc[ai][bj][m][0], v1 = acc[ai][bj][m][1];
;                         u32x4 w; w.x = cvt_pk(v0[0], v0[1]); w.y = cvt_pk(v0[2], v0[3]); w.z = cvt_pk(v1[0], v1[1]); w.w = cvt_pk(v1[2], v1[3]);
;                         *(u32x4*)(rowp + bj * HALF) = w; } }
	s_add_u32 s10, s14, 0x40080
	s_addc_u32 s11, s15, 0
	s_add_i32 s14, s36, s21
	s_mov_b32 m0, s14
	v_lshl_add_u64 v[160:161], s[10:11], 0, v[132:133]
	global_load_lds_dwordx4 v[160:161], off
	v_lshl_add_u64 v[160:161], s[10:11], 0, v[128:129]
	s_add_i32 m0, s14, 0x2000
	s_nop 0
	global_load_lds_dwordx4 v[160:161], off
	s_waitcnt vmcnt(6)
	s_barrier
	s_setprio 1
	v_mfma_f32_16x16x32_bf16 v[48:51], v[210:213], v[178:181], v[48:51]
	v_mfma_f32_16x16x32_bf16 v[40:43], v[218:221], v[178:181], v[40:43]
	v_mfma_f32_16x16x32_bf16 v[32:35], v[210:213], v[186:189], v[32:35]
	v_mfma_f32_16x16x32_bf16 v[24:27], v[218:221], v[186:189], v[24:27]
	v_mfma_f32_16x16x32_bf16 v[16:19], v[210:213], v[194:197], v[16:19]
	v_mfma_f32_16x16x32_bf16 v[8:11], v[218:221], v[194:197], v[8:11]
	v_mfma_f32_16x16x32_bf16 v[4:7], v[210:213], v[202:205], v[4:7]
	v_mfma_f32_16x16x32_bf16 v[0:3], v[218:221], v[202:205], v[0:3]
	v_mfma_f32_16x16x32_bf16 v[48:51], v[214:217], v[182:185], v[48:51]
	v_mfma_f32_16x16x32_bf16 v[40:43], v[222:225], v[182:185], v[40:43]
	v_mfma_f32_16x16x32_bf16 v[32:35], v[214:217], v[190:193], v[32:35]
	v_mfma_f32_16x16x32_bf16 v[24:27], v[222:225], v[190:193], v[24:27]
	v_mfma_f32_16x16x32_bf16 v[16:19], v[214:217], v[198:201], v[16:19]
	v_mfma_f32_16x16x32_bf16 v[8:11], v[222:225], v[198:201], v[8:11]
	v_mfma_f32_16x16x32_bf16 v[4:7], v[214:217], v[206:209], v[4:7]
	v_mfma_f32_16x16x32_bf16 v[0:3], v[222:225], v[206:209], v[0:3]
	s_setprio 0
	s_add_i32 s43, s43, 2
	s_add_u32 s41, s41, 0x100
	s_addc_u32 s42, s42, 0
	s_cmp_gt_u32 s43, 13
	s_mov_b64 s[10:11], s[12:13]
	s_barrier
	s_cbranch_scc0 .LBB0_74
	v_add_u32_e32 v136, s100, v157
	v_lshl_add_u64 v[160:161], v[138:139], 0, v[136:137]
	v_cvt_pk_bf16_f32 v124, v124, v125
	v_cvt_pk_bf16_f32 v125, v126, v127
	v_cvt_pk_bf16_f32 v126, v120, v121
	v_cvt_pk_bf16_f32 v127, v122, v123
	global_store_dwordx4 v[160:161], v[124:127], off sc1
	v_cvt_pk_bf16_f32 v112, v112, v113
	v_cvt_pk_bf16_f32 v113, v114, v115
	v_cvt_pk_bf16_f32 v114, v104, v105
	v_cvt_pk_bf16_f32 v115, v106, v107
	global_store_dwordx4 v[160:161], v[112:115], off offset:256 sc1
	v_cvt_pk_bf16_f32 v104, v116, v117
	v_cvt_pk_bf16_f32 v105, v118, v119
	v_cvt_pk_bf16_f32 v106, v108, v109
	v_cvt_pk_bf16_f32 v107, v110, v111
	s_cmp_eq_u32 s37, 12
	s_nop 0
	v_lshl_add_u64 v[112:113], v[140:141], 0, v[136:137]
	global_store_dwordx4 v[112:113], v[104:107], off sc1
	v_cvt_pk_bf16_f32 v96, v96, v97
	v_cvt_pk_bf16_f32 v97, v98, v99
	v_cvt_pk_bf16_f32 v98, v88, v89
	v_cvt_pk_bf16_f32 v99, v90, v91
	global_store_dwordx4 v[112:113], v[96:99], off offset:256 sc1
	v_cvt_pk_bf16_f32 v88, v100, v101
	v_cvt_pk_bf16_f32 v89, v102, v103
	v_cvt_pk_bf16_f32 v90, v92, v93
	v_cvt_pk_bf16_f32 v91, v94, v95
	s_mov_b32 s38, s37
	s_nop 0
	v_lshl_add_u64 v[96:97], v[142:143], 0, v[136:137]
	global_store_dwordx4 v[96:97], v[88:91], off sc1
	v_cvt_pk_bf16_f32 v80, v80, v81
	v_cvt_pk_bf16_f32 v81, v82, v83
	v_cvt_pk_bf16_f32 v82, v72, v73
	v_cvt_pk_bf16_f32 v83, v74, v75
	global_store_dwordx4 v[96:97], v[80:83], off offset:256 sc1
	v_cvt_pk_bf16_f32 v72, v84, v85
	v_cvt_pk_bf16_f32 v73, v86, v87
	v_cvt_pk_bf16_f32 v74, v76, v77
	v_cvt_pk_bf16_f32 v75, v78, v79
	s_mov_b64 s[10:11], s[8:9]
	s_nop 0
	v_lshl_add_u64 v[80:81], v[144:145], 0, v[136:137]
	global_store_dwordx4 v[80:81], v[72:75], off sc1
	v_cvt_pk_bf16_f32 v68, v68, v69
	v_cvt_pk_bf16_f32 v69, v70, v71
	v_cvt_pk_bf16_f32 v70, v64, v65
	v_lshl_add_u64 v[64:65], v[146:147], 0, v[136:137]
	v_cvt_pk_bf16_f32 v71, v66, v67
	global_store_dwordx4 v[80:81], v[68:71], off offset:256 sc1
	v_cvt_pk_bf16_f32 v60, v60, v61
	v_cvt_pk_bf16_f32 v61, v62, v63
	v_cvt_pk_bf16_f32 v62, v56, v57
	v_cvt_pk_bf16_f32 v63, v58, v59
	global_store_dwordx4 v[64:65], v[60:63], off sc1
	v_cvt_pk_bf16_f32 v48, v48, v49
	v_cvt_pk_bf16_f32 v49, v50, v51
	v_cvt_pk_bf16_f32 v50, v40, v41
	v_cvt_pk_bf16_f32 v51, v42, v43
	global_store_dwordx4 v[64:65], v[48:51], off offset:256 sc1
	v_cvt_pk_bf16_f32 v40, v52, v53
	v_cvt_pk_bf16_f32 v41, v54, v55
	v_cvt_pk_bf16_f32 v42, v44, v45
	v_cvt_pk_bf16_f32 v43, v46, v47
	s_nop 1
	v_lshl_add_u64 v[48:49], v[148:149], 0, v[136:137]
	global_store_dwordx4 v[48:49], v[40:43], off sc1
	v_cvt_pk_bf16_f32 v32, v32, v33
	v_cvt_pk_bf16_f32 v33, v34, v35
	v_cvt_pk_bf16_f32 v34, v24, v25
	v_cvt_pk_bf16_f32 v35, v26, v27
	global_store_dwordx4 v[48:49], v[32:35], off offset:256 sc1
	v_cvt_pk_bf16_f32 v24, v36, v37
	v_cvt_pk_bf16_f32 v25, v38, v39
	v_cvt_pk_bf16_f32 v26, v28, v29
	v_cvt_pk_bf16_f32 v27, v30, v31
	s_nop 1
	v_lshl_add_u64 v[32:33], v[150:151], 0, v[136:137]
	global_store_dwordx4 v[32:33], v[24:27], off sc1
	v_cvt_pk_bf16_f32 v16, v16, v17
	v_cvt_pk_bf16_f32 v17, v18, v19
	v_cvt_pk_bf16_f32 v18, v8, v9
	v_cvt_pk_bf16_f32 v19, v10, v11
	global_store_dwordx4 v[32:33], v[16:19], off offset:256 sc1
	v_cvt_pk_bf16_f32 v8, v20, v21
	v_cvt_pk_bf16_f32 v9, v22, v23
	v_cvt_pk_bf16_f32 v10, v12, v13
	v_cvt_pk_bf16_f32 v11, v14, v15
	s_nop 1
	v_lshl_add_u64 v[16:17], v[152:153], 0, v[136:137]
	global_store_dwordx4 v[16:17], v[8:11], off sc1
	v_cvt_pk_bf16_f32 v4, v4, v5
	v_cvt_pk_bf16_f32 v5, v6, v7
	v_cvt_pk_bf16_f32 v6, v0, v1
	v_cvt_pk_bf16_f32 v7, v2, v3
	global_store_dwordx4 v[16:17], v[4:7], off offset:256 sc1
	s_cbranch_scc0 .LBB0_73
	s_waitcnt vmcnt(0)
	s_cmpk_gt_u32 s20, 0xff
	s_cbranch_scc1 .LBB0_78
	s_barrier
